# P14 gain loads hoisted (no load->wait round trips at the kernel end); P11 state-item start rotated so the sample-norm workgroups take one item instead of two
# speedup vs baseline: 1.0014x; 1.0014x over previous
; #define LAS __attribute__((address_space(3)))
; __device__ __forceinline__ unsigned char* karg_ws() { return *(volatile KAS ucptr_t*)((const KAS char*)__builtin_amdgcn_kernarg_segment_ptr() + 264); }
; #define lane opq(lane_now())
; #define tid opq((wave << 6) | lane_now())
; template <int MODE>
; __device__ __forceinline__ void delta_sample_item(const Params& P, LAS unsigned char* lds, int item, int tid) {
;     LAS float* tmp = (LAS float*)lds;
;     LAS float* scl = (LAS float*)(lds + 1536);
;     LAS float* rpk = (LAS float*)(lds + 2048);
;     LAS float* rpq = (LAS float*)(lds + 4096);
;     const int bs = item >> 3, h = item & 7, lane = tid & 63, wave = tid >> 6; const size_t row = (size_t)MPR + bs;
;     const bf16* Zq = (const bf16*)(karg_ws() + WS_Z + 2 * ZB);
;     if (tid < 384) { const int which = tid >> 7, d = tid & 127; const int c3 = which * 1024 + h * 128 + d;
; __global__ void __launch_bounds__(NTHR, 2) fwd_megakernel(Params P) {
;     ...
;         for (int item = (G == 256 ? SS_TAIL : 0) + wg; item < NS * NH; item += G) delta_sample_item<1>(P, lds, item, tid);
.LBB0_2103:
	v_readlane_b32 s4, v238, 18
	v_readlane_b32 s5, v238, 19
	s_and_b64 s[4:5], exec, s[4:5]
	s_cselect_b32 s4, 0x212, 0
	s_add_i32 s3, s2, 0xf0
	s_and_b32 s3, s3, 0xff
	s_add_i32 s3, s4, s3
	s_cmpk_gt_i32 s3, 0x3ff
	s_mov_b32 s7, 0
	s_cbranch_scc1 .LBB0_2125
	s_mov_b32 s5, 0
	s_mov_b32 s4, s3
	s_lshl_b64 s[4:5], s[4:5], 16
	s_waitcnt lgkmcnt(0)
	s_add_u32 s12, s4, 0x46ebe00
	s_addc_u32 s13, s5, 0
	s_ashr_i32 s5, s78, 31
	s_mov_b32 s4, s78
	s_lshl_b64 s[14:15], s[4:5], 16
	s_movk_i32 s20, 0x180
	s_mov_b32 s21, 0x2040000
	v_mov_b32_e32 v1, 0
	s_mov_b32 s22, 0x90c0000
	s_mov_b32 s23, 0x9000
	s_movk_i32 s24, 0x3000
	s_movk_i32 s25, 0x6000
	s_mov_b32 s26, 0xfb915000
	s_mov_b32 s27, 0xfb916000
	s_mov_b32 s28, 0xfb917000
	s_mov_b32 s29, 0xfb918000
	v_mov_b32_e32 v12, 0x2e00000
	s_mov_b32 s30, 0x41a00000
	s_mov_b32 s31, 0x3f2aaaab
	v_mov_b32_e32 v13, 0x3ecc95a3
	s_mov_b32 s34, 0x3f317218
	s_mov_b32 s35, 0x7f800000
	s_mov_b32 s36, 0x33800000
	s_movk_i32 s37, 0xd000
	s_movk_i32 s38, 0xe000
	s_movk_i32 s39, 0xf000
	v_mov_b32_e32 v14, 0x300
	v_mov_b32_e32 v2, 0x3f317218
	v_mov_b32_e32 v15, 0x7f800000
	v_mov_b32_e32 v16, 0x7fc00000
	v_mov_b32_e32 v17, 0xff800000
	s_branch .LBB0_2106

; __device__ __forceinline__ unsigned pk2(float lo, float hi) { f32x2_t v = {lo, hi}; bf16x2_t b = __builtin_convertvector(v, bf16x2_t); return __builtin_bit_cast(unsigned, b); }
; __device__ __forceinline__ float rsq_f(float x) { return __builtin_amdgcn_rsqf(x); }
; __device__ __forceinline__ float* karg_out() { return *(volatile KAS fptr_t*)((const KAS char*)__builtin_amdgcn_kernarg_segment_ptr() + 256); }
; __device__ __forceinline__ unsigned char* karg_ws() { return *(volatile KAS ucptr_t*)((const KAS char*)__builtin_amdgcn_kernarg_segment_ptr() + 264); }
; #define lane opq(lane_now())
; template <int MODE>
; __device__ __forceinline__ void sample_norm_rows(const float* gvec, int ish, int gw, int lane) {
;     if (gw >= NS) return;
;     const int row = MPR + gw; float* X = karg_out() + (size_t)row * D;
;     f32x4 v[4]; float s = 0.f;
; #pragma unroll
;     for (int j = 0; j < 4; ++j) { v[j] = *(const f32x4*)(X + 4 * (lane + 64 * j)); s += (v[j][0] * v[j][0] + v[j][1] * v[j][1]) + (v[j][2] * v[j][2] + v[j][3] * v[j][3]); }
;     const float rstd = rsq_f(wave_sum(s) * (1.f / D) + EPS);
;     const float* sh = (const float*)(karg_ws() + WS_ADA) + (size_t)cond_of_row(row) * NADA + ish * D;
; #pragma unroll
;     for (int j = 0; j < 4; ++j) { const int col = 4 * (lane + 64 * j); const f32x4 g = *(const f32x4*)(gvec + col);
;         if (MODE == 0) { const f32x4 y = (v[j] * rstd * g) * (*(const f32x4*)(sh + D + col) + 1.f) + *(const f32x4*)(sh + col);
;             u32x2 o; o.x = pk2(y[0], y[1]); o.y = pk2(y[2], y[3]); *(u32x2*)((bf16*)(karg_ws() + WS_H) + (size_t)row * D + col) = o; }
;         else *(f32x4*)(X + col) = v[j] * rstd * g; }
.LBB0_2420:
	s_or_b64 exec, exec, s[2:3]
	s_waitcnt lgkmcnt(0)
	s_barrier
	s_load_dwordx2 s[2:3], s[0:1], 0xf8
	s_and_b64 vcc, exec, s[8:9]
	s_cbranch_vccnz .LBB0_2422
	s_load_dwordx2 s[4:5], s[0:1], 0x100
	s_ashr_i32 s71, s70, 31
	v_lshlrev_b32_e32 v0, 2, v166
	s_lshl_b64 s[6:7], s[70:71], 12
	v_ashrrev_i32_e32 v1, 31, v0
	s_waitcnt lgkmcnt(0)
	s_add_u32 s4, s4, s6
	s_addc_u32 s5, s5, s7
	v_lshlrev_b64 v[16:17], 2, v[0:1]
	v_lshl_add_u64 v[8:9], s[4:5], 0, v[16:17]
	s_mov_b64 s[4:5], 0x4000000
	v_lshl_add_u64 v[20:21], v[8:9], 0, s[4:5]
	v_add_co_u32_e32 v22, vcc, 0x4000000, v8
	global_load_dwordx4 v[0:3], v[20:21], off offset:1024
	global_load_dwordx4 v[4:7], v[20:21], off offset:2048
	v_addc_co_u32_e32 v23, vcc, 0, v9, vcc
	global_load_dwordx4 v[8:11], v[22:23], off
	global_load_dwordx4 v[12:15], v[20:21], off offset:3072
	v_lshl_add_u64 v[24:25], s[2:3], 0, v[16:17]
	s_load_dwordx2 s[0:1], s[0:1], 0x108
	global_load_dwordx4 v[16:19], v[24:25], off
	global_load_dwordx4 v[92:95], v[24:25], off offset:1024
	global_load_dwordx4 v[96:99], v[24:25], off offset:2048
	global_load_dwordx4 v[100:103], v[24:25], off offset:3072
	v_mov_b32_e32 v40, 0x358637bd
	s_waitcnt vmcnt(7)
	v_pk_mul_f32 v[26:27], v[2:3], v[2:3]
	v_pk_mul_f32 v[28:29], v[0:1], v[0:1]
	s_waitcnt vmcnt(6)
	v_mul_f32_e32 v30, v5, v5
	v_mul_f32_e32 v32, v7, v7
	s_waitcnt vmcnt(5)
	v_pk_mul_f32 v[34:35], v[10:11], v[10:11]
	v_pk_mul_f32 v[36:37], v[8:9], v[8:9]
	v_pk_mov_b32 v[38:39], v[28:29], v[26:27] op_sel:[1,0]
	v_mov_b32_e32 v29, v27
	s_waitcnt vmcnt(4)
	v_mul_f32_e32 v43, v14, v14
	v_mul_f32_e32 v44, v15, v15
	v_pk_fma_f32 v[26:27], v[4:5], v[4:5], v[30:31] op_sel_hi:[1,1,0]
	v_pk_fma_f32 v[30:31], v[6:7], v[6:7], v[32:33] op_sel_hi:[1,1,0]
	v_pk_mov_b32 v[32:33], v[36:37], v[34:35] op_sel:[1,0]
	v_mov_b32_e32 v37, v35
	v_pk_add_f32 v[28:29], v[38:39], v[28:29]
	v_mov_b32_e32 v27, v43
	v_mov_b32_e32 v31, v44
	v_pk_add_f32 v[32:33], v[32:33], v[36:37]
	v_mul_f32_e32 v41, v12, v12
	v_mul_f32_e32 v42, v13, v13
	v_pk_add_f32 v[28:29], v[28:29], v[28:29] op_sel:[0,1] op_sel_hi:[1,0]
	v_pk_add_f32 v[26:27], v[26:27], v[30:31]
	v_pk_add_f32 v[30:31], v[32:33], v[32:33] op_sel:[0,1] op_sel_hi:[1,0]
	v_mov_b32_e32 v29, v42
	v_mov_b32_e32 v31, v41
	v_pk_add_f32 v[28:29], v[30:31], v[28:29]
	s_nop 0
	v_pk_add_f32 v[26:27], v[28:29], v[26:27]
	s_nop 0
	v_add_f32_e32 v26, v26, v27
	s_nop 1
	v_add_f32_dpp v26, v26, v26 quad_perm:[1,0,3,2] row_mask:0xf bank_mask:0xf bound_ctrl:1
	s_nop 1
	v_add_f32_dpp v26, v26, v26 quad_perm:[2,3,0,1] row_mask:0xf bank_mask:0xf bound_ctrl:1
	s_nop 1
	v_add_f32_dpp v26, v26, v26 row_half_mirror row_mask:0xf bank_mask:0xf bound_ctrl:1
	s_nop 1
	v_add_f32_dpp v26, v26, v26 row_mirror row_mask:0xf bank_mask:0xf bound_ctrl:1
	s_nop 0
	v_readlane_b32 s2, v26, 16
	v_readlane_b32 s3, v26, 48
	s_waitcnt lgkmcnt(0)
	v_readlane_b32 s0, v26, 0
	v_readlane_b32 s1, v26, 32
	v_mov_b32_e32 v26, s2
	v_mov_b32_e32 v27, s3
	v_pk_add_f32 v[26:27], s[0:1], v[26:27]
	s_nop 0
	v_add_f32_e32 v26, v26, v27
	v_fmac_f32_e32 v40, 0x3a800000, v26
	v_rsq_f32_e32 v26, v40
	s_nop 0
	v_pk_mul_f32 v[8:9], v[8:9], v[26:27] op_sel_hi:[1,0]
	v_pk_mul_f32 v[10:11], v[10:11], v[26:27] op_sel_hi:[1,0]
	s_waitcnt vmcnt(3)
	v_pk_mul_f32 v[8:9], v[16:17], v[8:9]
	v_pk_mul_f32 v[10:11], v[18:19], v[10:11]
	global_store_dwordx4 v[22:23], v[8:11], off
	v_pk_mul_f32 v[2:3], v[2:3], v[26:27] op_sel_hi:[1,0]
	v_pk_mul_f32 v[0:1], v[0:1], v[26:27] op_sel_hi:[1,0]
	v_pk_mul_f32 v[6:7], v[6:7], v[26:27] op_sel_hi:[1,0]
	v_pk_mul_f32 v[4:5], v[4:5], v[26:27] op_sel_hi:[1,0]
	s_waitcnt vmcnt(3)
	v_pk_mul_f32 v[0:1], v[92:93], v[0:1]
	v_pk_mul_f32 v[2:3], v[94:95], v[2:3]
	global_store_dwordx4 v[20:21], v[0:3], off offset:1024
	s_waitcnt vmcnt(3)
	v_pk_mul_f32 v[4:5], v[96:97], v[4:5]
	v_pk_mul_f32 v[6:7], v[98:99], v[6:7]
	global_store_dwordx4 v[20:21], v[4:7], off offset:2048
	v_pk_mul_f32 v[104:105], v[14:15], v[26:27] op_sel_hi:[1,0]
	v_pk_mul_f32 v[106:107], v[12:13], v[26:27] op_sel_hi:[1,0]
	s_waitcnt vmcnt(3)
	v_pk_mul_f32 v[110:111], v[102:103], v[104:105]
	v_pk_mul_f32 v[108:109], v[100:101], v[106:107]
	global_store_dwordx4 v[20:21], v[108:111], off offset:3072
